# SSD scan phase: static s_setprio 1 for waves 4-7 (the state-update helper waves, younger half), reset at phase exit; on top of the conv and GEMM raises
# speedup vs baseline: 1.0064x; 1.0064x over previous
; DI void scan_phase(PPtr p, int j, ldsp lds, int tid, int wave, int lane) {
;     const bf16_t* xT = (const bf16_t*)(p->ws + WS_XT); const bf16_t* Bc = (const bf16_t*)(p->ws + WS_BC); const bf16_t* Cc = (const bf16_t*)(p->ws + WS_CC);
;     const bf16_t* BT = (const bf16_t*)(p->ws + WS_BT); const float* dtraw = (const float*)(p->ws + WS_DTRAW); bf16_t* Y = (bf16_t*)(p->ws + WS_Y);
;     constexpr int PT = 136, PB = PT * 2;
;     constexpr int O_C = 0, O_B = 128 * PB, O_BT = 2 * 128 * PB, O_X = 3 * 128 * PB, O_XW = O_X + 32 * PB, O_S = O_XW + 32 * PB, O_DT = O_S + 32 * PB, O_AC = O_DT + 8 * 512;
;     LAS float* s_dt = (LAS float*)(lds + O_DT + wave * 512); LAS float* s_ac = (LAS float*)(lds + O_AC + wave * 512);
;     const int r = lane & 31, hi = lane >> 5;
;     for (int unit0 = blockIdx.x; unit0 < 256; unit0 += gridDim.x) {
;         const int unit = (gridDim.x == 256) ? ((unit0 & 7) * 32 + (unit0 >> 3)) : unit0;
;         const int b = unit >> 6, h = (unit >> 1) & 31, ph = unit & 1, g = h >> 3;
;         const float A = -__expf(p->ssd_a_log[j * SSDH + h]); const float dtb = p->ssd_dt_bias[j * SSDH + h]; const float Dh = p->ssd_d[j * SSDH + h];
;         f32x16 accS;
; #pragma unroll
;         for (int i = 0; i < 16; ++i) accS[i] = 0.f;
;         for (int i = tid; i < 32 * PB / 4; i += 512) *(LAS unsigned*)(lds + O_S + i * 4) = 0u;
;         u32x4 rc[4], rb[4], rbt[4], rx; float dr0, dr1;
;         const unsigned offRow = (unsigned)((tid >> 4) * 512 + (tid & 15) * 8), offT = (unsigned)((tid >> 4) * SEQ + (tid & 15) * 8);
;         const bf16_t* cBase = Cc + (size_t)b * SEQ * 512 + g * 128; const bf16_t* bBase = Bc + (size_t)b * SEQ * 512 + g * 128;
;         const bf16_t* btBase = BT + ((size_t)b * 512 + g * 128) * SEQ; const bf16_t* xBase = xT + ((size_t)b * 2048 + h * 64 + ph * 32) * SEQ;
;         const float* dBase = dtraw + (size_t)b * SEQ * 32 + h;
;     ...
;                 for (int off = 1; off < 64; off <<= 1) { const float n0 = __shfl_up(v0, off), n1 = __shfl_up(v1, off); if (lane >= off) { v0 += n0; v1 += n1; } }
;                 v1 += __shfl(v0, 63);
;                 s_dt[lane] = d0; s_dt[lane + 64] = d1; s_ac[lane] = v0; s_ac[lane + 64] = v1;
;             }
; #pragma unroll
;             for (int k = 0; k < 4; ++k) { const int id = tid + 512 * k, row = id >> 4, ch = id & 15; const int off = (row * PT + ch * 8) * 2;
.LBB0_637:
	s_or_b64 exec, exec, s[0:1]
	v_readlane_b32 s0, v254, 15
	v_mov_b32_e32 v132, v153
	v_readlane_b32 s1, v254, 16
	s_waitcnt lgkmcnt(0)
	s_barrier
	s_andn2_b64 vcc, exec, s[0:1]
	v_readfirstlane_b32 s2, v132
	s_cbranch_vccnz .LBB0_673
	v_readfirstlane_b32 s32, v153
	s_nop 3
	s_lshr_b32 s32, s32, 6
	s_cmp_ge_u32 s32, 4
	s_cbranch_scc0 .Lscan_prio_skip
	s_setprio 1
.Lscan_prio_skip:
	s_load_dwordx2 s[0:1], s[52:53], 0xc8
	v_lshlrev_b32_e32 v0, 3, v132
	v_ashrrev_i32_e32 v6, 4, v132
	v_and_b32_e32 v14, 0x78, v0
	v_lshl_or_b32 v134, v6, 12, v14
	s_waitcnt lgkmcnt(0)
	s_add_u32 s3, s0, 0x1b440000
	v_writelane_b32 v255, s3, 5
	s_addc_u32 s3, s1, 0
	v_writelane_b32 v255, s3, 6
	s_add_u32 s3, s0, 0x1c440000
	v_writelane_b32 v255, s3, 7
	s_addc_u32 s3, s1, 0
	v_writelane_b32 v255, s3, 8
	s_add_u32 s3, s0, 0x1d440000
	v_writelane_b32 v255, s3, 9
	s_addc_u32 s3, s1, 0
	v_writelane_b32 v255, s3, 10
	s_add_u32 s3, s0, 0x17240000
	v_writelane_b32 v255, s3, 11
	s_addc_u32 s3, s1, 0
	v_writelane_b32 v255, s3, 12
	s_add_u32 s3, s0, 0x1e440000
	v_mov_b32_e32 v135, v1
	v_writelane_b32 v255, s3, 13
	s_addc_u32 s3, s1, 0
	v_lshl_add_u64 v[12:13], v[134:135], 1, s[0:1]
	s_mov_b64 s[0:1], 0x17440000
	v_lshl_add_u64 v[144:145], v[12:13], 0, s[0:1]
	v_add_u32_e32 v12, -1, v204
	v_and_b32_e32 v13, 64, v204
	v_cmp_lt_i32_e32 vcc, v12, v13
	s_ashr_i32 s2, s2, 6
	v_writelane_b32 v255, s3, 14
	v_cndmask_b32_e32 v12, v12, v204, vcc
	v_lshlrev_b32_e32 v175, 2, v12
	v_add_u32_e32 v12, -2, v204
	v_cmp_lt_i32_e32 vcc, v12, v13
	s_lshl_b32 s3, s2, 9
	s_add_i32 s4, s3, 0
	v_cndmask_b32_e32 v12, v12, v204, vcc
	v_lshlrev_b32_e32 v176, 2, v12
	v_add_u32_e32 v12, -4, v204
	v_cmp_lt_i32_e32 vcc, v12, v13
	s_add_i32 s33, s4, 0x20e00
	s_add_i32 s6, s4, 0x1fe00
	v_cndmask_b32_e32 v12, v12, v204, vcc
	s_movk_i32 s4, 0x880
	v_lshlrev_b32_e32 v177, 2, v12
	v_add_u32_e32 v12, -8, v204
	v_cmp_gt_i32_e64 s[4:5], s4, v132
	v_cmp_lt_i32_e32 vcc, v12, v13
	s_cmp_gt_i32 s2, 3
	v_writelane_b32 v255, s4, 15
	v_cndmask_b32_e32 v12, v12, v204, vcc
	v_lshlrev_b32_e32 v178, 2, v12
	v_writelane_b32 v255, s5, 16
	s_cselect_b64 s[4:5], -1, 0
	s_lshl_b32 s19, s2, 5
	v_add_u32_e32 v12, -16, v204
	s_add_i32 s7, s19, 0xffffff80
	v_cmp_lt_i32_e32 vcc, v12, v13
	v_and_b32_e32 v3, 31, v132
	v_bfrev_b32_e32 v7, 0.5
	s_movk_i32 s20, 0x88
	s_cmp_gt_i32 s2, 5
	v_cndmask_b32_e32 v12, v12, v204, vcc
	v_and_b32_e32 v137, 63, v132
	v_lshl_or_b32 v0, v6, 9, v14
	v_lshl_or_b32 v164, v204, 2, v7
	v_mul_lo_u32 v6, v6, s20
	v_or_b32_e32 v7, s7, v3
	s_cselect_b64 s[8:9], -1, 0
	v_or_b32_e32 v171, s19, v3
	v_lshlrev_b32_e32 v179, 2, v12
	v_subrev_u32_e32 v12, 32, v204
	v_lshlrev_b32_e32 v165, 2, v137
	v_add_lshl_u32 v167, v6, v14, 1
	v_lshlrev_b32_e32 v6, 2, v14
	v_mul_lo_u32 v17, v7, s20
	v_writelane_b32 v255, s8, 17
	v_lshl_add_u32 v170, v7, 2, s33
	v_lshlrev_b32_e32 v7, 2, v171
	s_cmp_gt_i32 s2, 0
	v_cmp_lt_i32_e32 vcc, v12, v13
	v_add_u32_e32 v166, s6, v165
	v_add_u32_e32 v168, s6, v6
	v_writelane_b32 v255, s9, 18
	v_add_u32_e32 v173, s6, v7
	s_cselect_b64 s[6:7], -1, 0
	v_cndmask_b32_e32 v12, v12, v204, vcc
	v_add_u32_e32 v133, 0x200, v132
	v_writelane_b32 v255, s6, 19
	v_lshlrev_b32_e32 v180, 2, v12
	v_ashrrev_i32_e32 v12, 4, v133
	v_writelane_b32 v255, s7, 20
	s_lshl_b32 s6, s2, 7
	v_mul_lo_u32 v12, v12, s20
	v_add_u32_e32 v169, s33, v6
	v_or_b32_e32 v6, 0x1fffffe0, v132
	s_add_i32 s6, s33, s6
	v_add_lshl_u32 v181, v12, v14, 1
	v_add_u32_e32 v12, 0x400, v132
	v_bfe_u32 v5, v132, 5, 1
	v_mul_u32_u24_e32 v15, 0x88, v3
	v_add_u32_e32 v6, s19, v6
	s_addk_i32 s6, 0xff80
	v_ashrrev_i32_e32 v12, 4, v12
	v_lshlrev_b32_e32 v16, 3, v5
	v_mul_lo_u32 v19, v6, s20
	v_writelane_b32 v255, s6, 21
	v_add_lshl_u32 v6, s19, v15, 1
	v_readlane_b32 s6, v254, 31
	v_mul_lo_u32 v12, v12, s20
	s_cmp_gt_i32 s2, 1
	v_add3_u32 v174, s6, v16, v6
	s_movk_i32 s6, 0x220
	v_add_lshl_u32 v182, v12, v14, 1
	v_add_u32_e32 v12, 0x600, v132
	v_mad_u32_u24 v20, v5, s6, v171
	s_cselect_b64 s[6:7], -1, 0
	s_lshl_b32 s18, s2, 12
	v_ashrrev_i32_e32 v12, 4, v12
	v_mul_lo_u32 v18, v171, s20
	v_writelane_b32 v255, s6, 22
	v_mul_lo_u32 v12, v12, s20
	s_add_i32 s0, s18, 0xffffa000
	v_readlane_b32 s20, v254, 32
	v_writelane_b32 v255, s7, 23
	s_add_i32 s1, s20, s0
	s_add_i32 s0, s0, 0
	v_writelane_b32 v255, s1, 24
	s_add_i32 s1, s0, 0x21f00
	v_writelane_b32 v255, s1, 25
	s_add_i32 s1, s0, 0x22000
	v_writelane_b32 v255, s1, 26
	s_add_i32 s1, s0, 0x22100
	v_writelane_b32 v255, s1, 27
	s_add_i32 s1, s0, 0x22200
	v_writelane_b32 v255, s1, 28
	s_add_i32 s1, s0, 0x22300
	v_writelane_b32 v255, s1, 29
	s_add_i32 s1, s0, 0x22400
	v_writelane_b32 v255, s1, 30
	s_add_i32 s1, s0, 0x22500
	v_writelane_b32 v255, s1, 31
	s_add_i32 s1, s0, 0x22600
	v_writelane_b32 v255, s1, 32
	s_add_i32 s1, s0, 0x22700
	v_writelane_b32 v255, s1, 33
	s_add_i32 s1, s0, 0x22800
	v_writelane_b32 v255, s1, 34
	s_add_i32 s1, s0, 0x22900
	v_writelane_b32 v255, s1, 35
	s_add_i32 s1, s0, 0x22a00
	v_writelane_b32 v255, s1, 36
	s_add_i32 s1, s0, 0x22b00
	v_writelane_b32 v255, s1, 37
	s_add_i32 s1, s0, 0x22c00
	v_writelane_b32 v255, s1, 38
	s_add_i32 s0, s0, 0x22d00
; #define LAS __attribute__((address_space(3)))
; DI void scan_phase(PPtr p, int j, ldsp lds, int tid, int wave, int lane) {
;     ...
;         const int b = unit >> 6, h = (unit >> 1) & 31, ph = unit & 1, g = h >> 3;
;         const float A = -__expf(p->ssd_a_log[j * SSDH + h]); const float dtb = p->ssd_dt_bias[j * SSDH + h]; const float Dh = p->ssd_d[j * SSDH + h];
;         f32x16 accS;
; #pragma unroll
;         for (int i = 0; i < 16; ++i) accS[i] = 0.f;
;         for (int i = tid; i < 32 * PB / 4; i += 512) *(LAS unsigned*)(lds + O_S + i * 4) = 0u;
;         u32x4 rc[4], rb[4], rbt[4], rx; float dr0, dr1;
;         const unsigned offRow = (unsigned)((tid >> 4) * 512 + (tid & 15) * 8), offT = (unsigned)((tid >> 4) * SEQ + (tid & 15) * 8);
;         const bf16_t* cBase = Cc + (size_t)b * SEQ * 512 + g * 128; const bf16_t* bBase = Bc + (size_t)b * SEQ * 512 + g * 128;
;         const bf16_t* btBase = BT + ((size_t)b * 512 + g * 128) * SEQ; const bf16_t* xBase = xT + ((size_t)b * 2048 + h * 64 + ph * 32) * SEQ;
;         const float* dBase = dtraw + (size_t)b * SEQ * 32 + h;
	v_lshlrev_b32_e32 v136, 4, v5
	v_writelane_b32 v255, s0, 39
	s_movk_i32 s0, 0x110
	v_add_lshl_u32 v183, v12, v14, 1
	v_mad_u64_u32 v[12:13], s[0:1], v171, s0, v[136:137]
	v_lshlrev_b32_e32 v14, 2, v5
	v_cmp_gt_u32_e64 s[0:1], v14, v3
	v_or_b32_e32 v5, s19, v14
	v_mov_b32_e32 v27, 0xffffff00
	v_writelane_b32 v255, s0, 40
	s_add_i32 s18, s18, s20
	v_or_b32_e32 v13, 1, v5
	v_writelane_b32 v255, s1, 41
	v_cmp_gt_u32_e64 s[0:1], v3, v14
	v_lshl_add_u32 v20, v20, 1, v27
	v_add_u32_e32 v27, s18, v165
	v_writelane_b32 v255, s0, 42
	v_add_u32_e32 v188, 0xffffe000, v27
	v_add_u32_e32 v189, 0xffffe100, v27
	v_writelane_b32 v255, s1, 43
	v_cmp_eq_u32_e64 s[0:1], v13, v171
	v_add_u32_e32 v190, 0xffffe200, v27
	v_add_u32_e32 v191, 0xffffe300, v27
	v_add_u32_e32 v192, 0xffffe400, v27
	v_add_u32_e32 v193, 0xffffe500, v27
	v_add_u32_e32 v194, 0xffffe600, v27
	v_add_u32_e32 v195, 0xffffe700, v27
	v_add_u32_e32 v196, 0xffffe800, v27
	v_add_u32_e32 v197, 0xffffe900, v27
	v_add_u32_e32 v198, 0xffffea00, v27
	v_add_u32_e32 v199, 0xffffeb00, v27
	v_add_u32_e32 v218, 0xffffec00, v27
	v_add_u32_e32 v219, 0xffffed00, v27
	v_add_u32_e32 v220, 0xffffee00, v27
	v_add_u32_e32 v221, 0xffffef00, v27
	v_max_i32_e32 v27, 0x680, v132
	v_writelane_b32 v255, s0, 44
	v_sub_u32_e32 v27, v27, v132
	v_cmp_eq_u32_e64 s[24:25], v14, v3
	v_writelane_b32 v255, s1, 45
	v_add_u32_e32 v27, 0x1ff, v27
	s_movk_i32 s0, 0x1ff
	v_mul_u32_u24_e32 v3, 0x110, v3
	s_mov_b32 s1, 0x8800
	v_lshrrev_b32_e32 v28, 9, v27
	v_add3_u32 v223, v3, v136, s1
	v_cmp_lt_u32_e64 s[0:1], s0, v27
	v_add_u32_e32 v28, 1, v28
	v_and_b32_e32 v224, 0xfffffe, v28
	v_writelane_b32 v255, s0, 46
	s_mov_b64 s[92:93], s[52:53]
	v_or_b32_e32 v222, s3, v136
	v_writelane_b32 v255, s1, 47
	s_add_i32 s0, s2, -5
	v_writelane_b32 v255, s0, 48
	v_cmp_ne_u32_e64 s[0:1], v28, v224
	v_or_b32_e32 v13, 3, v5
	v_or_b32_e32 v21, 2, v5
	v_writelane_b32 v255, s0, 49
	v_cmp_gt_i32_e64 s[26:27], v13, v171
	v_cmp_gt_i32_e64 s[28:29], v21, v171
	v_writelane_b32 v255, s1, 50
	s_load_dwordx2 s[0:1], s[92:93], 0xa8
	v_cmp_eq_u32_e64 s[30:31], v13, v171
	v_cmp_eq_u32_e64 s[34:35], v21, v171
	v_or_b32_e32 v13, 9, v5
	v_or_b32_e32 v21, 8, v5
	s_waitcnt lgkmcnt(0)
	v_writelane_b32 v255, s0, 51
	v_lshlrev_b32_e32 v2, 5, v137
	v_lshl_add_u32 v185, v21, 2, s33
	v_writelane_b32 v255, s1, 52
	v_writelane_b32 v255, s92, 53
	s_load_dwordx4 s[0:3], s[92:93], 0x98
	v_cmp_gt_i32_e64 s[36:37], v13, v171
	v_writelane_b32 v255, s93, 54
	v_cmp_gt_i32_e64 s[38:39], v21, v171
	v_cmp_eq_u32_e64 s[40:41], v13, v171
	s_waitcnt lgkmcnt(0)
	v_writelane_b32 v255, s0, 55
	v_cmp_eq_u32_e64 s[42:43], v21, v171
	v_or_b32_e32 v13, 11, v5
	v_or_b32_e32 v21, 10, v5
	v_writelane_b32 v255, s1, 56
	v_or_b32_e32 v4, 0x800, v2
	v_add_u32_e32 v172, s33, v7
	v_add_u32_e32 v6, 0x4000, v0
	v_mov_b32_e32 v7, v1
	v_add_u32_e32 v8, 0x8000, v0
	v_mov_b32_e32 v9, v1
	v_add_u32_e32 v10, 0xc000, v0
	v_mov_b32_e32 v11, v1
	v_add_lshl_u32 v15, v16, v15, 1
	v_add_lshl_u32 v17, v17, v16, 1
	v_add_lshl_u32 v18, v18, v16, 1
	v_add_lshl_u32 v19, v19, v16, 1
	v_lshl_add_u32 v184, v5, 2, s33
	v_cmp_gt_i32_e64 s[44:45], v13, v171
	v_cmp_gt_i32_e64 s[46:47], v21, v171
	v_cmp_eq_u32_e64 s[48:49], v13, v171
	v_cmp_eq_u32_e64 s[50:51], v21, v171
	v_or_b32_e32 v13, 17, v5
	v_or_b32_e32 v21, 16, v5
	v_or_b32_e32 v22, 19, v5
	v_or_b32_e32 v23, 18, v5
	v_or_b32_e32 v24, 25, v5
	v_or_b32_e32 v25, 24, v5
	v_or_b32_e32 v26, 27, v5
	v_or_b32_e32 v5, 26, v5
	v_lshlrev_b32_e32 v226, 2, v2
	v_add_u32_e32 v2, 0, v20
	v_writelane_b32 v255, s2, 57
	v_add_u32_e32 v138, 0x20000, v134
	v_mov_b32_e32 v139, v1
	v_add_u32_e32 v140, 0x40000, v134
	v_mov_b32_e32 v141, v1
	v_add_u32_e32 v142, 0x60000, v134
	v_mov_b32_e32 v143, v1
	v_cmp_eq_u32_e64 s[6:7], 0, v137
	v_cmp_gt_u32_e64 s[8:9], 2, v137
	v_cmp_gt_u32_e64 s[10:11], 4, v137
	v_cmp_gt_u32_e64 s[12:13], 8, v137
	v_cmp_gt_u32_e64 s[14:15], 16, v137
	v_cmp_gt_u32_e64 s[16:17], 32, v137
	v_lshl_add_u32 v186, v21, 2, s33
	v_cmp_gt_i32_e64 s[52:53], v13, v171
	v_cmp_gt_i32_e64 s[54:55], v21, v171
	v_lshl_add_u32 v187, v25, 2, s33
	v_or_b32_e32 v225, v3, v16
	v_lshlrev_b32_e32 v227, 2, v4
	v_lshlrev_b32_e32 v146, 1, v14
	v_add_u32_e32 v228, 0, v19
	v_add_u32_e32 v229, 0, v12
	v_add_u32_e32 v230, 0x1dc00, v2
	v_lshlrev_b64 v[148:149], 1, v[0:1]
	v_lshlrev_b64 v[150:151], 1, v[6:7]
	v_lshlrev_b64 v[156:157], 1, v[8:9]
	v_lshlrev_b64 v[158:159], 1, v[10:11]
	v_add_u32_e32 v231, 0, v15
	v_add_u32_e32 v232, 0, v17
	v_add_u32_e32 v233, 0, v18
	s_mov_b32 s23, s64
	v_cmp_eq_u32_e64 s[58:59], v13, v171
	v_cmp_eq_u32_e64 s[60:61], v21, v171
	v_cmp_gt_i32_e64 s[62:63], v22, v171
	v_cmp_gt_i32_e64 s[64:65], v23, v171
	v_cmp_eq_u32_e64 s[66:67], v22, v171
	v_cmp_eq_u32_e64 s[68:69], v23, v171
	v_cmp_gt_i32_e64 s[70:71], v24, v171
	v_cmp_gt_i32_e64 s[72:73], v25, v171
	v_cmp_eq_u32_e64 s[74:75], v24, v171
	v_cmp_eq_u32_e64 s[76:77], v25, v171
	v_cmp_gt_i32_e64 s[78:79], v26, v171
	v_cmp_gt_i32_e64 s[80:81], v5, v171
	v_cmp_eq_u32_e64 s[82:83], v26, v171
	v_cmp_eq_u32_e64 s[84:85], v5, v171
	v_writelane_b32 v255, s3, 58
	s_branch .LBB0_640

; #define LAS __attribute__((address_space(3)))
; DI unsigned xb_xcc_id() { return (unsigned)__builtin_amdgcn_s_getreg((3 << 11) | 20) & 0xFu; }
; DI void xcd_barrier(unsigned* bar_, volatile LAS unsigned* st_) {
;     XcdBarrier b; b.bar = bar_; b.st = st_; b.x = 0;
;     asm volatile("s_waitcnt vmcnt(0)" ::: "memory");
;     __syncthreads();
;     if (threadIdx.x == 0) {
;         unsigned* bar = b.bar; b.x = xb_xcc_id();
;         __builtin_amdgcn_s_waitcnt(0);
;         unsigned nloc = b.st[0], nx = b.st[1];
;         if (nloc == 0u) { xcd_barrier_complete(bar, b.x, nloc, nx); b.st[0] = nloc; b.st[1] = nx; }
.LBB0_673:
	s_setprio 0
	s_waitcnt vmcnt(0)
	s_barrier
	s_and_saveexec_b64 s[0:1], s[66:67]
	s_cbranch_execz .LBB0_725
	v_readlane_b32 s5, v254, 28
	s_load_dwordx2 s[2:3], s[52:53], 0xc8
	s_getreg_b32 s4, hwreg(HW_REG_XCC_ID, 0, 4)
	v_mov_b32_e32 v0, s5
	s_waitcnt vmcnt(0) expcnt(0) lgkmcnt(0)
	ds_read_b32 v3, v0
	v_readlane_b32 s5, v254, 29
	s_and_b32 s18, s4, 15
	s_waitcnt lgkmcnt(0)
	v_cmp_ne_u32_e32 vcc, 0, v3
	v_mov_b32_e32 v0, s5
	ds_read_b32 v2, v0
	s_cbranch_vccnz .LBB0_689
	s_add_u32 s4, s2, 0x1000
	s_addc_u32 s5, s3, 0
	s_add_u32 s6, s2, 0x1100
	s_addc_u32 s7, s3, 0
	s_add_u32 s8, s2, 0x1200
	s_addc_u32 s9, s3, 0
	s_add_u32 s10, s2, 0x1300
	s_addc_u32 s11, s3, 0
	s_mov_b32 s19, 1
	s_branch .LBB0_677
